# ph0 modulation vectors: the serialized one-at-a-time weight loads become 16-deep double-buffered batches (unrolled), silu prologue issues its 20 loads at once
# speedup vs baseline: 1.0196x; 1.0196x over previous
.LBB0_858:
	s_or_b64 exec, exec, s[44:45]
	v_mov_b32_e32 v4, v168
	s_movk_i32 s1, 0x1400
	s_waitcnt lgkmcnt(0)
	v_cmp_gt_i32_e32 vcc, s1, v4
	s_barrier
	s_and_saveexec_b64 s[36:37], vcc
	s_cbranch_execz .LBB0_865
	v_lshlrev_b32_e32 v3, 2, v4
	v_add_u32_e32 v5, 0x1000, v3
	v_add_u32_e32 v6, 0x2000, v3
	v_add_u32_e32 v7, 0x3000, v3
	global_load_dword v60, v3, s[6:7]
	global_load_dword v61, v3, s[6:7] offset:1024
	global_load_dword v62, v3, s[6:7] offset:2048
	global_load_dword v63, v3, s[6:7] offset:3072
	global_load_dword v64, v3, s[4:5]
	global_load_dword v65, v3, s[4:5] offset:1024
	global_load_dword v66, v3, s[4:5] offset:2048
	global_load_dword v67, v3, s[4:5] offset:3072
	global_load_dword v68, v5, s[4:5]
	global_load_dword v69, v5, s[4:5] offset:1024
	global_load_dword v70, v5, s[4:5] offset:2048
	global_load_dword v71, v5, s[4:5] offset:3072
	global_load_dword v72, v6, s[4:5]
	global_load_dword v73, v6, s[4:5] offset:1024
	global_load_dword v74, v6, s[4:5] offset:2048
	global_load_dword v75, v6, s[4:5] offset:3072
	global_load_dword v76, v7, s[4:5]
	global_load_dword v77, v7, s[4:5] offset:1024
	global_load_dword v78, v7, s[4:5] offset:2048
	global_load_dword v79, v7, s[4:5] offset:3072
	s_waitcnt vmcnt(19)
	v_mul_f32_e32 v80, 0xbfb8aa3b, v60
	v_exp_f32_e32 v80, v80
	s_nop 0
	v_add_f32_e32 v80, 1.0, v80
	v_rcp_f32_e32 v80, v80
	s_nop 0
	v_mul_f32_e32 v80, v60, v80
	ds_write_b32 v3, v80
	s_waitcnt vmcnt(18)
	v_mul_f32_e32 v81, 0xbfb8aa3b, v61
	v_exp_f32_e32 v81, v81
	s_nop 0
	v_add_f32_e32 v81, 1.0, v81
	v_rcp_f32_e32 v81, v81
	s_nop 0
	v_mul_f32_e32 v81, v61, v81
	ds_write_b32 v3, v81 offset:1024
	s_waitcnt vmcnt(17)
	v_mul_f32_e32 v82, 0xbfb8aa3b, v62
	v_exp_f32_e32 v82, v82
	s_nop 0
	v_add_f32_e32 v82, 1.0, v82
	v_rcp_f32_e32 v82, v82
	s_nop 0
	v_mul_f32_e32 v82, v62, v82
	ds_write_b32 v3, v82 offset:2048
	s_waitcnt vmcnt(16)
	v_mul_f32_e32 v83, 0xbfb8aa3b, v63
	v_exp_f32_e32 v83, v83
	s_nop 0
	v_add_f32_e32 v83, 1.0, v83
	v_rcp_f32_e32 v83, v83
	s_nop 0
	v_mul_f32_e32 v83, v63, v83
	ds_write_b32 v3, v83 offset:3072
	s_waitcnt vmcnt(15)
	v_mul_f32_e32 v84, 0xbfb8aa3b, v64
	v_exp_f32_e32 v84, v84
	s_nop 0
	v_add_f32_e32 v84, 1.0, v84
	v_rcp_f32_e32 v84, v84
	s_nop 0
	v_mul_f32_e32 v84, v64, v84
	ds_write_b32 v3, v84 offset:4096
	s_waitcnt vmcnt(14)
	v_mul_f32_e32 v85, 0xbfb8aa3b, v65
	v_exp_f32_e32 v85, v85
	s_nop 0
	v_add_f32_e32 v85, 1.0, v85
	v_rcp_f32_e32 v85, v85
	s_nop 0
	v_mul_f32_e32 v85, v65, v85
	ds_write_b32 v3, v85 offset:5120
	s_waitcnt vmcnt(13)
	v_mul_f32_e32 v86, 0xbfb8aa3b, v66
	v_exp_f32_e32 v86, v86
	s_nop 0
	v_add_f32_e32 v86, 1.0, v86
	v_rcp_f32_e32 v86, v86
	s_nop 0
	v_mul_f32_e32 v86, v66, v86
	ds_write_b32 v3, v86 offset:6144
	s_waitcnt vmcnt(12)
	v_mul_f32_e32 v87, 0xbfb8aa3b, v67
	v_exp_f32_e32 v87, v87
	s_nop 0
	v_add_f32_e32 v87, 1.0, v87
	v_rcp_f32_e32 v87, v87
	s_nop 0
	v_mul_f32_e32 v87, v67, v87
	ds_write_b32 v3, v87 offset:7168
	s_waitcnt vmcnt(11)
	v_mul_f32_e32 v88, 0xbfb8aa3b, v68
	v_exp_f32_e32 v88, v88
	s_nop 0
	v_add_f32_e32 v88, 1.0, v88
	v_rcp_f32_e32 v88, v88
	s_nop 0
	v_mul_f32_e32 v88, v68, v88
	ds_write_b32 v3, v88 offset:8192
	s_waitcnt vmcnt(10)
	v_mul_f32_e32 v89, 0xbfb8aa3b, v69
	v_exp_f32_e32 v89, v89
	s_nop 0
	v_add_f32_e32 v89, 1.0, v89
	v_rcp_f32_e32 v89, v89
	s_nop 0
	v_mul_f32_e32 v89, v69, v89
	ds_write_b32 v3, v89 offset:9216
	s_waitcnt vmcnt(9)
	v_mul_f32_e32 v90, 0xbfb8aa3b, v70
	v_exp_f32_e32 v90, v90
	s_nop 0
	v_add_f32_e32 v90, 1.0, v90
	v_rcp_f32_e32 v90, v90
	s_nop 0
	v_mul_f32_e32 v90, v70, v90
	ds_write_b32 v3, v90 offset:10240
	s_waitcnt vmcnt(8)
	v_mul_f32_e32 v91, 0xbfb8aa3b, v71
	v_exp_f32_e32 v91, v91
	s_nop 0
	v_add_f32_e32 v91, 1.0, v91
	v_rcp_f32_e32 v91, v91
	s_nop 0
	v_mul_f32_e32 v91, v71, v91
	ds_write_b32 v3, v91 offset:11264
	s_waitcnt vmcnt(7)
	v_mul_f32_e32 v92, 0xbfb8aa3b, v72
	v_exp_f32_e32 v92, v92
	s_nop 0
	v_add_f32_e32 v92, 1.0, v92
	v_rcp_f32_e32 v92, v92
	s_nop 0
	v_mul_f32_e32 v92, v72, v92
	ds_write_b32 v3, v92 offset:12288
	s_waitcnt vmcnt(6)
	v_mul_f32_e32 v93, 0xbfb8aa3b, v73
	v_exp_f32_e32 v93, v93
	s_nop 0
	v_add_f32_e32 v93, 1.0, v93
	v_rcp_f32_e32 v93, v93
	s_nop 0
	v_mul_f32_e32 v93, v73, v93
	ds_write_b32 v3, v93 offset:13312
	s_waitcnt vmcnt(5)
	v_mul_f32_e32 v94, 0xbfb8aa3b, v74
	v_exp_f32_e32 v94, v94
	s_nop 0
	v_add_f32_e32 v94, 1.0, v94
	v_rcp_f32_e32 v94, v94
	s_nop 0
	v_mul_f32_e32 v94, v74, v94
	ds_write_b32 v3, v94 offset:14336
	s_waitcnt vmcnt(4)
	v_mul_f32_e32 v95, 0xbfb8aa3b, v75
	v_exp_f32_e32 v95, v95
	s_nop 0
	v_add_f32_e32 v95, 1.0, v95
	v_rcp_f32_e32 v95, v95
	s_nop 0
	v_mul_f32_e32 v95, v75, v95
	ds_write_b32 v3, v95 offset:15360
	s_waitcnt vmcnt(3)
	v_mul_f32_e32 v96, 0xbfb8aa3b, v76
	v_exp_f32_e32 v96, v96
	s_nop 0
	v_add_f32_e32 v96, 1.0, v96
	v_rcp_f32_e32 v96, v96
	s_nop 0
	v_mul_f32_e32 v96, v76, v96
	ds_write_b32 v3, v96 offset:16384
	s_waitcnt vmcnt(2)
	v_mul_f32_e32 v97, 0xbfb8aa3b, v77
	v_exp_f32_e32 v97, v97
	s_nop 0
	v_add_f32_e32 v97, 1.0, v97
	v_rcp_f32_e32 v97, v97
	s_nop 0
	v_mul_f32_e32 v97, v77, v97
	ds_write_b32 v3, v97 offset:17408
	s_waitcnt vmcnt(1)
	v_mul_f32_e32 v98, 0xbfb8aa3b, v78
	v_exp_f32_e32 v98, v98
	s_nop 0
	v_add_f32_e32 v98, 1.0, v98
	v_rcp_f32_e32 v98, v98
	s_nop 0
	v_mul_f32_e32 v98, v78, v98
	ds_write_b32 v3, v98 offset:18432
	s_waitcnt vmcnt(0)
	v_mul_f32_e32 v99, 0xbfb8aa3b, v79
	v_exp_f32_e32 v99, v99
	s_nop 0
	v_add_f32_e32 v99, 1.0, v99
	v_rcp_f32_e32 v99, v99
	s_nop 0
	v_mul_f32_e32 v99, v79, v99
	ds_write_b32 v3, v99 offset:19456

.LBB0_869:
	s_waitcnt vmcnt(0)
	global_load_dword v60, v[20:21], off
	s_mov_b64 s[2:3], 0x6000
	v_lshl_add_u64 v[94:95], v[20:21], 0, s[2:3]
	global_load_dword v61, v[94:95], off
	s_mov_b64 s[2:3], 0xc000
	v_lshl_add_u64 v[96:97], v[20:21], 0, s[2:3]
	global_load_dword v62, v[96:97], off
	s_mov_b64 s[2:3], 0x12000
	v_lshl_add_u64 v[98:99], v[20:21], 0, s[2:3]
	global_load_dword v63, v[98:99], off
	s_mov_b64 s[2:3], 0x18000
	v_lshl_add_u64 v[100:101], v[20:21], 0, s[2:3]
	global_load_dword v64, v[100:101], off
	s_mov_b64 s[2:3], 0x1e000
	v_lshl_add_u64 v[102:103], v[20:21], 0, s[2:3]
	global_load_dword v65, v[102:103], off
	s_mov_b64 s[2:3], 0x24000
	v_lshl_add_u64 v[104:105], v[20:21], 0, s[2:3]
	global_load_dword v66, v[104:105], off
	s_mov_b64 s[2:3], 0x2a000
	v_lshl_add_u64 v[106:107], v[20:21], 0, s[2:3]
	global_load_dword v67, v[106:107], off
	s_mov_b64 s[2:3], 0x30000
	v_lshl_add_u64 v[108:109], v[20:21], 0, s[2:3]
	global_load_dword v68, v[108:109], off
	s_mov_b64 s[2:3], 0x36000
	v_lshl_add_u64 v[110:111], v[20:21], 0, s[2:3]
	global_load_dword v69, v[110:111], off
	s_mov_b64 s[2:3], 0x3c000
	v_lshl_add_u64 v[112:113], v[20:21], 0, s[2:3]
	global_load_dword v70, v[112:113], off
	s_mov_b64 s[2:3], 0x42000
	v_lshl_add_u64 v[114:115], v[20:21], 0, s[2:3]
	global_load_dword v71, v[114:115], off
	s_mov_b64 s[2:3], 0x48000
	v_lshl_add_u64 v[116:117], v[20:21], 0, s[2:3]
	global_load_dword v72, v[116:117], off
	s_mov_b64 s[2:3], 0x4e000
	v_lshl_add_u64 v[118:119], v[20:21], 0, s[2:3]
	global_load_dword v73, v[118:119], off
	s_mov_b64 s[2:3], 0x54000
	v_lshl_add_u64 v[120:121], v[20:21], 0, s[2:3]
	global_load_dword v74, v[120:121], off
	s_mov_b64 s[2:3], 0x5a000
	v_lshl_add_u64 v[122:123], v[20:21], 0, s[2:3]
	global_load_dword v75, v[122:123], off
	s_mov_b64 s[2:3], 0x60000
	v_lshl_add_u64 v[92:93], v[20:21], 0, s[2:3]
	global_load_dword v76, v[92:93], off
	s_mov_b64 s[2:3], 0x66000
	v_lshl_add_u64 v[94:95], v[20:21], 0, s[2:3]
	global_load_dword v77, v[94:95], off
	s_mov_b64 s[2:3], 0x6c000
	v_lshl_add_u64 v[96:97], v[20:21], 0, s[2:3]
	global_load_dword v78, v[96:97], off
	s_mov_b64 s[2:3], 0x72000
	v_lshl_add_u64 v[98:99], v[20:21], 0, s[2:3]
	global_load_dword v79, v[98:99], off
	s_mov_b64 s[2:3], 0x78000
	v_lshl_add_u64 v[100:101], v[20:21], 0, s[2:3]
	global_load_dword v80, v[100:101], off
	s_mov_b64 s[2:3], 0x7e000
	v_lshl_add_u64 v[102:103], v[20:21], 0, s[2:3]
	global_load_dword v81, v[102:103], off
	s_mov_b64 s[2:3], 0x84000
	v_lshl_add_u64 v[104:105], v[20:21], 0, s[2:3]
	global_load_dword v82, v[104:105], off
	s_mov_b64 s[2:3], 0x8a000
	v_lshl_add_u64 v[106:107], v[20:21], 0, s[2:3]
	global_load_dword v83, v[106:107], off
	s_mov_b64 s[2:3], 0x90000
	v_lshl_add_u64 v[108:109], v[20:21], 0, s[2:3]
	global_load_dword v84, v[108:109], off
	s_mov_b64 s[2:3], 0x96000
	v_lshl_add_u64 v[110:111], v[20:21], 0, s[2:3]
	global_load_dword v85, v[110:111], off
	s_mov_b64 s[2:3], 0x9c000
	v_lshl_add_u64 v[112:113], v[20:21], 0, s[2:3]
	global_load_dword v86, v[112:113], off
	s_mov_b64 s[2:3], 0xa2000
	v_lshl_add_u64 v[114:115], v[20:21], 0, s[2:3]
	global_load_dword v87, v[114:115], off
	s_mov_b64 s[2:3], 0xa8000
	v_lshl_add_u64 v[116:117], v[20:21], 0, s[2:3]
	global_load_dword v88, v[116:117], off
	s_mov_b64 s[2:3], 0xae000
	v_lshl_add_u64 v[118:119], v[20:21], 0, s[2:3]
	global_load_dword v89, v[118:119], off
	s_mov_b64 s[2:3], 0xb4000
	v_lshl_add_u64 v[120:121], v[20:21], 0, s[2:3]
	global_load_dword v90, v[120:121], off
	s_mov_b64 s[2:3], 0xba000
	v_lshl_add_u64 v[122:123], v[20:21], 0, s[2:3]
	global_load_dword v91, v[122:123], off
	ds_read_b128 v[32:35], v30
	ds_read_b128 v[36:39], v30 offset:4096
	ds_read_b128 v[40:43], v30 offset:8192
	ds_read_b128 v[44:47], v30 offset:12288
	ds_read_b128 v[48:51], v30 offset:16384
	s_waitcnt lgkmcnt(0)
	s_waitcnt vmcnt(31)
	v_fmac_f32_e32 v24, v60, v32
	v_fmac_f32_e32 v29, v60, v36
	v_fmac_f32_e32 v27, v60, v40
	v_fmac_f32_e32 v26, v60, v44
	v_fmac_f32_e32 v25, v60, v48
	s_waitcnt vmcnt(30)
	v_fmac_f32_e32 v24, v61, v33
	v_fmac_f32_e32 v29, v61, v37
	v_fmac_f32_e32 v27, v61, v41
	v_fmac_f32_e32 v26, v61, v45
	v_fmac_f32_e32 v25, v61, v49
	s_waitcnt vmcnt(29)
	v_fmac_f32_e32 v24, v62, v34
	v_fmac_f32_e32 v29, v62, v38
	v_fmac_f32_e32 v27, v62, v42
	v_fmac_f32_e32 v26, v62, v46
	v_fmac_f32_e32 v25, v62, v50
	s_waitcnt vmcnt(28)
	v_fmac_f32_e32 v24, v63, v35
	v_fmac_f32_e32 v29, v63, v39
	v_fmac_f32_e32 v27, v63, v43
	v_fmac_f32_e32 v26, v63, v47
	v_fmac_f32_e32 v25, v63, v51
	ds_read_b128 v[32:35], v30 offset:16
	ds_read_b128 v[36:39], v30 offset:4112
	ds_read_b128 v[40:43], v30 offset:8208
	ds_read_b128 v[44:47], v30 offset:12304
	ds_read_b128 v[48:51], v30 offset:16400
	s_waitcnt lgkmcnt(0)
	s_waitcnt vmcnt(27)
	v_fmac_f32_e32 v24, v64, v32
	v_fmac_f32_e32 v29, v64, v36
	v_fmac_f32_e32 v27, v64, v40
	v_fmac_f32_e32 v26, v64, v44
	v_fmac_f32_e32 v25, v64, v48
	s_waitcnt vmcnt(26)
	v_fmac_f32_e32 v24, v65, v33
	v_fmac_f32_e32 v29, v65, v37
	v_fmac_f32_e32 v27, v65, v41
	v_fmac_f32_e32 v26, v65, v45
	v_fmac_f32_e32 v25, v65, v49
	s_waitcnt vmcnt(25)
	v_fmac_f32_e32 v24, v66, v34
	v_fmac_f32_e32 v29, v66, v38
	v_fmac_f32_e32 v27, v66, v42
	v_fmac_f32_e32 v26, v66, v46
	v_fmac_f32_e32 v25, v66, v50
	s_waitcnt vmcnt(24)
	v_fmac_f32_e32 v24, v67, v35
	v_fmac_f32_e32 v29, v67, v39
	v_fmac_f32_e32 v27, v67, v43
	v_fmac_f32_e32 v26, v67, v47
	v_fmac_f32_e32 v25, v67, v51
	ds_read_b128 v[32:35], v30 offset:32
	ds_read_b128 v[36:39], v30 offset:4128
	ds_read_b128 v[40:43], v30 offset:8224
	ds_read_b128 v[44:47], v30 offset:12320
	ds_read_b128 v[48:51], v30 offset:16416
	s_waitcnt lgkmcnt(0)
	s_waitcnt vmcnt(23)
	v_fmac_f32_e32 v24, v68, v32
	v_fmac_f32_e32 v29, v68, v36
	v_fmac_f32_e32 v27, v68, v40
	v_fmac_f32_e32 v26, v68, v44
	v_fmac_f32_e32 v25, v68, v48
	s_waitcnt vmcnt(22)
	v_fmac_f32_e32 v24, v69, v33
	v_fmac_f32_e32 v29, v69, v37
	v_fmac_f32_e32 v27, v69, v41
	v_fmac_f32_e32 v26, v69, v45
	v_fmac_f32_e32 v25, v69, v49
	s_waitcnt vmcnt(21)
	v_fmac_f32_e32 v24, v70, v34
	v_fmac_f32_e32 v29, v70, v38
	v_fmac_f32_e32 v27, v70, v42
	v_fmac_f32_e32 v26, v70, v46
	v_fmac_f32_e32 v25, v70, v50
	s_waitcnt vmcnt(20)
	v_fmac_f32_e32 v24, v71, v35
	v_fmac_f32_e32 v29, v71, v39
	v_fmac_f32_e32 v27, v71, v43
	v_fmac_f32_e32 v26, v71, v47
	v_fmac_f32_e32 v25, v71, v51
	ds_read_b128 v[32:35], v30 offset:48
	ds_read_b128 v[36:39], v30 offset:4144
	ds_read_b128 v[40:43], v30 offset:8240
	ds_read_b128 v[44:47], v30 offset:12336
	ds_read_b128 v[48:51], v30 offset:16432
	s_waitcnt lgkmcnt(0)
	s_waitcnt vmcnt(19)
	v_fmac_f32_e32 v24, v72, v32
	v_fmac_f32_e32 v29, v72, v36
	v_fmac_f32_e32 v27, v72, v40
	v_fmac_f32_e32 v26, v72, v44
	v_fmac_f32_e32 v25, v72, v48
	s_waitcnt vmcnt(18)
	v_fmac_f32_e32 v24, v73, v33
	v_fmac_f32_e32 v29, v73, v37
	v_fmac_f32_e32 v27, v73, v41
	v_fmac_f32_e32 v26, v73, v45
	v_fmac_f32_e32 v25, v73, v49
	s_waitcnt vmcnt(17)
	v_fmac_f32_e32 v24, v74, v34
	v_fmac_f32_e32 v29, v74, v38
	v_fmac_f32_e32 v27, v74, v42
	v_fmac_f32_e32 v26, v74, v46
	v_fmac_f32_e32 v25, v74, v50
	s_waitcnt vmcnt(16)
	v_fmac_f32_e32 v24, v75, v35
	v_fmac_f32_e32 v29, v75, v39
	v_fmac_f32_e32 v27, v75, v43
	v_fmac_f32_e32 v26, v75, v47
	v_fmac_f32_e32 v25, v75, v51
	s_mov_b64 s[2:3], 0xc0000
	v_lshl_add_u64 v[92:93], v[20:21], 0, s[2:3]
	global_load_dword v60, v[92:93], off
	s_mov_b64 s[2:3], 0xc6000
	v_lshl_add_u64 v[94:95], v[20:21], 0, s[2:3]
	global_load_dword v61, v[94:95], off
	s_mov_b64 s[2:3], 0xcc000
	v_lshl_add_u64 v[96:97], v[20:21], 0, s[2:3]
	global_load_dword v62, v[96:97], off
	s_mov_b64 s[2:3], 0xd2000
	v_lshl_add_u64 v[98:99], v[20:21], 0, s[2:3]
	global_load_dword v63, v[98:99], off
	s_mov_b64 s[2:3], 0xd8000
	v_lshl_add_u64 v[100:101], v[20:21], 0, s[2:3]
	global_load_dword v64, v[100:101], off
	s_mov_b64 s[2:3], 0xde000
	v_lshl_add_u64 v[102:103], v[20:21], 0, s[2:3]
	global_load_dword v65, v[102:103], off
	s_mov_b64 s[2:3], 0xe4000
	v_lshl_add_u64 v[104:105], v[20:21], 0, s[2:3]
	global_load_dword v66, v[104:105], off
	s_mov_b64 s[2:3], 0xea000
	v_lshl_add_u64 v[106:107], v[20:21], 0, s[2:3]
	global_load_dword v67, v[106:107], off
	s_mov_b64 s[2:3], 0xf0000
	v_lshl_add_u64 v[108:109], v[20:21], 0, s[2:3]
	global_load_dword v68, v[108:109], off
	s_mov_b64 s[2:3], 0xf6000
	v_lshl_add_u64 v[110:111], v[20:21], 0, s[2:3]
	global_load_dword v69, v[110:111], off
	s_mov_b64 s[2:3], 0xfc000
	v_lshl_add_u64 v[112:113], v[20:21], 0, s[2:3]
	global_load_dword v70, v[112:113], off
	s_mov_b64 s[2:3], 0x102000
	v_lshl_add_u64 v[114:115], v[20:21], 0, s[2:3]
	global_load_dword v71, v[114:115], off
	s_mov_b64 s[2:3], 0x108000
	v_lshl_add_u64 v[116:117], v[20:21], 0, s[2:3]
	global_load_dword v72, v[116:117], off
	s_mov_b64 s[2:3], 0x10e000
	v_lshl_add_u64 v[118:119], v[20:21], 0, s[2:3]
	global_load_dword v73, v[118:119], off
	s_mov_b64 s[2:3], 0x114000
	v_lshl_add_u64 v[120:121], v[20:21], 0, s[2:3]
	global_load_dword v74, v[120:121], off
	s_mov_b64 s[2:3], 0x11a000
	v_lshl_add_u64 v[122:123], v[20:21], 0, s[2:3]
	global_load_dword v75, v[122:123], off
	ds_read_b128 v[32:35], v30 offset:64
	ds_read_b128 v[36:39], v30 offset:4160
	ds_read_b128 v[40:43], v30 offset:8256
	ds_read_b128 v[44:47], v30 offset:12352
	ds_read_b128 v[48:51], v30 offset:16448
	s_waitcnt lgkmcnt(0)
	s_waitcnt vmcnt(31)
	v_fmac_f32_e32 v24, v76, v32
	v_fmac_f32_e32 v29, v76, v36
	v_fmac_f32_e32 v27, v76, v40
	v_fmac_f32_e32 v26, v76, v44
	v_fmac_f32_e32 v25, v76, v48
	s_waitcnt vmcnt(30)
	v_fmac_f32_e32 v24, v77, v33
	v_fmac_f32_e32 v29, v77, v37
	v_fmac_f32_e32 v27, v77, v41
	v_fmac_f32_e32 v26, v77, v45
	v_fmac_f32_e32 v25, v77, v49
	s_waitcnt vmcnt(29)
	v_fmac_f32_e32 v24, v78, v34
	v_fmac_f32_e32 v29, v78, v38
	v_fmac_f32_e32 v27, v78, v42
	v_fmac_f32_e32 v26, v78, v46
	v_fmac_f32_e32 v25, v78, v50
	s_waitcnt vmcnt(28)
	v_fmac_f32_e32 v24, v79, v35
	v_fmac_f32_e32 v29, v79, v39
	v_fmac_f32_e32 v27, v79, v43
	v_fmac_f32_e32 v26, v79, v47
	v_fmac_f32_e32 v25, v79, v51
	ds_read_b128 v[32:35], v30 offset:80
	ds_read_b128 v[36:39], v30 offset:4176
	ds_read_b128 v[40:43], v30 offset:8272
	ds_read_b128 v[44:47], v30 offset:12368
	ds_read_b128 v[48:51], v30 offset:16464
	s_waitcnt lgkmcnt(0)
	s_waitcnt vmcnt(27)
	v_fmac_f32_e32 v24, v80, v32
	v_fmac_f32_e32 v29, v80, v36
	v_fmac_f32_e32 v27, v80, v40
	v_fmac_f32_e32 v26, v80, v44
	v_fmac_f32_e32 v25, v80, v48
	s_waitcnt vmcnt(26)
	v_fmac_f32_e32 v24, v81, v33
	v_fmac_f32_e32 v29, v81, v37
	v_fmac_f32_e32 v27, v81, v41
	v_fmac_f32_e32 v26, v81, v45
	v_fmac_f32_e32 v25, v81, v49
	s_waitcnt vmcnt(25)
	v_fmac_f32_e32 v24, v82, v34
	v_fmac_f32_e32 v29, v82, v38
	v_fmac_f32_e32 v27, v82, v42
	v_fmac_f32_e32 v26, v82, v46
	v_fmac_f32_e32 v25, v82, v50
	s_waitcnt vmcnt(24)
	v_fmac_f32_e32 v24, v83, v35
	v_fmac_f32_e32 v29, v83, v39
	v_fmac_f32_e32 v27, v83, v43
	v_fmac_f32_e32 v26, v83, v47
	v_fmac_f32_e32 v25, v83, v51
	ds_read_b128 v[32:35], v30 offset:96
	ds_read_b128 v[36:39], v30 offset:4192
	ds_read_b128 v[40:43], v30 offset:8288
	ds_read_b128 v[44:47], v30 offset:12384
	ds_read_b128 v[48:51], v30 offset:16480
	s_waitcnt lgkmcnt(0)
	s_waitcnt vmcnt(23)
	v_fmac_f32_e32 v24, v84, v32
	v_fmac_f32_e32 v29, v84, v36
	v_fmac_f32_e32 v27, v84, v40
	v_fmac_f32_e32 v26, v84, v44
	v_fmac_f32_e32 v25, v84, v48
	s_waitcnt vmcnt(22)
	v_fmac_f32_e32 v24, v85, v33
	v_fmac_f32_e32 v29, v85, v37
	v_fmac_f32_e32 v27, v85, v41
	v_fmac_f32_e32 v26, v85, v45
	v_fmac_f32_e32 v25, v85, v49
	s_waitcnt vmcnt(21)
	v_fmac_f32_e32 v24, v86, v34
	v_fmac_f32_e32 v29, v86, v38
	v_fmac_f32_e32 v27, v86, v42
	v_fmac_f32_e32 v26, v86, v46
	v_fmac_f32_e32 v25, v86, v50
	s_waitcnt vmcnt(20)
	v_fmac_f32_e32 v24, v87, v35
	v_fmac_f32_e32 v29, v87, v39
	v_fmac_f32_e32 v27, v87, v43
	v_fmac_f32_e32 v26, v87, v47
	v_fmac_f32_e32 v25, v87, v51
	ds_read_b128 v[32:35], v30 offset:112
	ds_read_b128 v[36:39], v30 offset:4208
	ds_read_b128 v[40:43], v30 offset:8304
	ds_read_b128 v[44:47], v30 offset:12400
	ds_read_b128 v[48:51], v30 offset:16496
	s_waitcnt lgkmcnt(0)
	s_waitcnt vmcnt(19)
	v_fmac_f32_e32 v24, v88, v32
	v_fmac_f32_e32 v29, v88, v36
	v_fmac_f32_e32 v27, v88, v40
	v_fmac_f32_e32 v26, v88, v44
	v_fmac_f32_e32 v25, v88, v48
	s_waitcnt vmcnt(18)
	v_fmac_f32_e32 v24, v89, v33
	v_fmac_f32_e32 v29, v89, v37
	v_fmac_f32_e32 v27, v89, v41
	v_fmac_f32_e32 v26, v89, v45
	v_fmac_f32_e32 v25, v89, v49
	s_waitcnt vmcnt(17)
	v_fmac_f32_e32 v24, v90, v34
	v_fmac_f32_e32 v29, v90, v38
	v_fmac_f32_e32 v27, v90, v42
	v_fmac_f32_e32 v26, v90, v46
	v_fmac_f32_e32 v25, v90, v50
	s_waitcnt vmcnt(16)
	v_fmac_f32_e32 v24, v91, v35
	v_fmac_f32_e32 v29, v91, v39
	v_fmac_f32_e32 v27, v91, v43
	v_fmac_f32_e32 v26, v91, v47
	v_fmac_f32_e32 v25, v91, v51
	s_mov_b64 s[2:3], 0x120000
	v_lshl_add_u64 v[92:93], v[20:21], 0, s[2:3]
	global_load_dword v76, v[92:93], off
	s_mov_b64 s[2:3], 0x126000
	v_lshl_add_u64 v[94:95], v[20:21], 0, s[2:3]
	global_load_dword v77, v[94:95], off
	s_mov_b64 s[2:3], 0x12c000
	v_lshl_add_u64 v[96:97], v[20:21], 0, s[2:3]
	global_load_dword v78, v[96:97], off
	s_mov_b64 s[2:3], 0x132000
	v_lshl_add_u64 v[98:99], v[20:21], 0, s[2:3]
	global_load_dword v79, v[98:99], off
	s_mov_b64 s[2:3], 0x138000
	v_lshl_add_u64 v[100:101], v[20:21], 0, s[2:3]
	global_load_dword v80, v[100:101], off
	s_mov_b64 s[2:3], 0x13e000
	v_lshl_add_u64 v[102:103], v[20:21], 0, s[2:3]
	global_load_dword v81, v[102:103], off
	s_mov_b64 s[2:3], 0x144000
	v_lshl_add_u64 v[104:105], v[20:21], 0, s[2:3]
	global_load_dword v82, v[104:105], off
	s_mov_b64 s[2:3], 0x14a000
	v_lshl_add_u64 v[106:107], v[20:21], 0, s[2:3]
	global_load_dword v83, v[106:107], off
	s_mov_b64 s[2:3], 0x150000
	v_lshl_add_u64 v[108:109], v[20:21], 0, s[2:3]
	global_load_dword v84, v[108:109], off
	s_mov_b64 s[2:3], 0x156000
	v_lshl_add_u64 v[110:111], v[20:21], 0, s[2:3]
	global_load_dword v85, v[110:111], off
	s_mov_b64 s[2:3], 0x15c000
	v_lshl_add_u64 v[112:113], v[20:21], 0, s[2:3]
	global_load_dword v86, v[112:113], off
	s_mov_b64 s[2:3], 0x162000
	v_lshl_add_u64 v[114:115], v[20:21], 0, s[2:3]
	global_load_dword v87, v[114:115], off
	s_mov_b64 s[2:3], 0x168000
	v_lshl_add_u64 v[116:117], v[20:21], 0, s[2:3]
	global_load_dword v88, v[116:117], off
	s_mov_b64 s[2:3], 0x16e000
	v_lshl_add_u64 v[118:119], v[20:21], 0, s[2:3]
	global_load_dword v89, v[118:119], off
	s_mov_b64 s[2:3], 0x174000
	v_lshl_add_u64 v[120:121], v[20:21], 0, s[2:3]
	global_load_dword v90, v[120:121], off
	s_mov_b64 s[2:3], 0x17a000
	v_lshl_add_u64 v[122:123], v[20:21], 0, s[2:3]
	global_load_dword v91, v[122:123], off
	ds_read_b128 v[32:35], v30 offset:128
	ds_read_b128 v[36:39], v30 offset:4224
	ds_read_b128 v[40:43], v30 offset:8320
	ds_read_b128 v[44:47], v30 offset:12416
	ds_read_b128 v[48:51], v30 offset:16512
	s_waitcnt lgkmcnt(0)
	s_waitcnt vmcnt(31)
	v_fmac_f32_e32 v24, v60, v32
	v_fmac_f32_e32 v29, v60, v36
	v_fmac_f32_e32 v27, v60, v40
	v_fmac_f32_e32 v26, v60, v44
	v_fmac_f32_e32 v25, v60, v48
	s_waitcnt vmcnt(30)
	v_fmac_f32_e32 v24, v61, v33
	v_fmac_f32_e32 v29, v61, v37
	v_fmac_f32_e32 v27, v61, v41
	v_fmac_f32_e32 v26, v61, v45
	v_fmac_f32_e32 v25, v61, v49
	s_waitcnt vmcnt(29)
	v_fmac_f32_e32 v24, v62, v34
	v_fmac_f32_e32 v29, v62, v38
	v_fmac_f32_e32 v27, v62, v42
	v_fmac_f32_e32 v26, v62, v46
	v_fmac_f32_e32 v25, v62, v50
	s_waitcnt vmcnt(28)
	v_fmac_f32_e32 v24, v63, v35
	v_fmac_f32_e32 v29, v63, v39
	v_fmac_f32_e32 v27, v63, v43
	v_fmac_f32_e32 v26, v63, v47
	v_fmac_f32_e32 v25, v63, v51
	ds_read_b128 v[32:35], v30 offset:144
	ds_read_b128 v[36:39], v30 offset:4240
	ds_read_b128 v[40:43], v30 offset:8336
	ds_read_b128 v[44:47], v30 offset:12432
	ds_read_b128 v[48:51], v30 offset:16528
	s_waitcnt lgkmcnt(0)
	s_waitcnt vmcnt(27)
	v_fmac_f32_e32 v24, v64, v32
	v_fmac_f32_e32 v29, v64, v36
	v_fmac_f32_e32 v27, v64, v40
	v_fmac_f32_e32 v26, v64, v44
	v_fmac_f32_e32 v25, v64, v48
	s_waitcnt vmcnt(26)
	v_fmac_f32_e32 v24, v65, v33
	v_fmac_f32_e32 v29, v65, v37
	v_fmac_f32_e32 v27, v65, v41
	v_fmac_f32_e32 v26, v65, v45
	v_fmac_f32_e32 v25, v65, v49
	s_waitcnt vmcnt(25)
	v_fmac_f32_e32 v24, v66, v34
	v_fmac_f32_e32 v29, v66, v38
	v_fmac_f32_e32 v27, v66, v42
	v_fmac_f32_e32 v26, v66, v46
	v_fmac_f32_e32 v25, v66, v50
	s_waitcnt vmcnt(24)
	v_fmac_f32_e32 v24, v67, v35
	v_fmac_f32_e32 v29, v67, v39
	v_fmac_f32_e32 v27, v67, v43
	v_fmac_f32_e32 v26, v67, v47
	v_fmac_f32_e32 v25, v67, v51
	ds_read_b128 v[32:35], v30 offset:160
	ds_read_b128 v[36:39], v30 offset:4256
	ds_read_b128 v[40:43], v30 offset:8352
	ds_read_b128 v[44:47], v30 offset:12448
	ds_read_b128 v[48:51], v30 offset:16544
	s_waitcnt lgkmcnt(0)
	s_waitcnt vmcnt(23)
	v_fmac_f32_e32 v24, v68, v32
	v_fmac_f32_e32 v29, v68, v36
	v_fmac_f32_e32 v27, v68, v40
	v_fmac_f32_e32 v26, v68, v44
	v_fmac_f32_e32 v25, v68, v48
	s_waitcnt vmcnt(22)
	v_fmac_f32_e32 v24, v69, v33
	v_fmac_f32_e32 v29, v69, v37
	v_fmac_f32_e32 v27, v69, v41
	v_fmac_f32_e32 v26, v69, v45
	v_fmac_f32_e32 v25, v69, v49
	s_waitcnt vmcnt(21)
	v_fmac_f32_e32 v24, v70, v34
	v_fmac_f32_e32 v29, v70, v38
	v_fmac_f32_e32 v27, v70, v42
	v_fmac_f32_e32 v26, v70, v46
	v_fmac_f32_e32 v25, v70, v50
	s_waitcnt vmcnt(20)
	v_fmac_f32_e32 v24, v71, v35
	v_fmac_f32_e32 v29, v71, v39
	v_fmac_f32_e32 v27, v71, v43
	v_fmac_f32_e32 v26, v71, v47
	v_fmac_f32_e32 v25, v71, v51
	ds_read_b128 v[32:35], v30 offset:176
	ds_read_b128 v[36:39], v30 offset:4272
	ds_read_b128 v[40:43], v30 offset:8368
	ds_read_b128 v[44:47], v30 offset:12464
	ds_read_b128 v[48:51], v30 offset:16560
	s_waitcnt lgkmcnt(0)
	s_waitcnt vmcnt(19)
	v_fmac_f32_e32 v24, v72, v32
	v_fmac_f32_e32 v29, v72, v36
	v_fmac_f32_e32 v27, v72, v40
	v_fmac_f32_e32 v26, v72, v44
	v_fmac_f32_e32 v25, v72, v48
	s_waitcnt vmcnt(18)
	v_fmac_f32_e32 v24, v73, v33
	v_fmac_f32_e32 v29, v73, v37
	v_fmac_f32_e32 v27, v73, v41
	v_fmac_f32_e32 v26, v73, v45
	v_fmac_f32_e32 v25, v73, v49
	s_waitcnt vmcnt(17)
	v_fmac_f32_e32 v24, v74, v34
	v_fmac_f32_e32 v29, v74, v38
	v_fmac_f32_e32 v27, v74, v42
	v_fmac_f32_e32 v26, v74, v46
	v_fmac_f32_e32 v25, v74, v50
	s_waitcnt vmcnt(16)
	v_fmac_f32_e32 v24, v75, v35
	v_fmac_f32_e32 v29, v75, v39
	v_fmac_f32_e32 v27, v75, v43
	v_fmac_f32_e32 v26, v75, v47
	v_fmac_f32_e32 v25, v75, v51
	s_mov_b64 s[2:3], 0x180000
	v_lshl_add_u64 v[92:93], v[20:21], 0, s[2:3]
	global_load_dword v60, v[92:93], off
	s_mov_b64 s[2:3], 0x186000
	v_lshl_add_u64 v[94:95], v[20:21], 0, s[2:3]
	global_load_dword v61, v[94:95], off
	s_mov_b64 s[2:3], 0x18c000
	v_lshl_add_u64 v[96:97], v[20:21], 0, s[2:3]
	global_load_dword v62, v[96:97], off
	s_mov_b64 s[2:3], 0x192000
	v_lshl_add_u64 v[98:99], v[20:21], 0, s[2:3]
	global_load_dword v63, v[98:99], off
	s_mov_b64 s[2:3], 0x198000
	v_lshl_add_u64 v[100:101], v[20:21], 0, s[2:3]
	global_load_dword v64, v[100:101], off
	s_mov_b64 s[2:3], 0x19e000
	v_lshl_add_u64 v[102:103], v[20:21], 0, s[2:3]
	global_load_dword v65, v[102:103], off
	s_mov_b64 s[2:3], 0x1a4000
	v_lshl_add_u64 v[104:105], v[20:21], 0, s[2:3]
	global_load_dword v66, v[104:105], off
	s_mov_b64 s[2:3], 0x1aa000
	v_lshl_add_u64 v[106:107], v[20:21], 0, s[2:3]
	global_load_dword v67, v[106:107], off
	s_mov_b64 s[2:3], 0x1b0000
	v_lshl_add_u64 v[108:109], v[20:21], 0, s[2:3]
	global_load_dword v68, v[108:109], off
	s_mov_b64 s[2:3], 0x1b6000
	v_lshl_add_u64 v[110:111], v[20:21], 0, s[2:3]
	global_load_dword v69, v[110:111], off
	s_mov_b64 s[2:3], 0x1bc000
	v_lshl_add_u64 v[112:113], v[20:21], 0, s[2:3]
	global_load_dword v70, v[112:113], off
	s_mov_b64 s[2:3], 0x1c2000
	v_lshl_add_u64 v[114:115], v[20:21], 0, s[2:3]
	global_load_dword v71, v[114:115], off
	s_mov_b64 s[2:3], 0x1c8000
	v_lshl_add_u64 v[116:117], v[20:21], 0, s[2:3]
	global_load_dword v72, v[116:117], off
	s_mov_b64 s[2:3], 0x1ce000
	v_lshl_add_u64 v[118:119], v[20:21], 0, s[2:3]
	global_load_dword v73, v[118:119], off
	s_mov_b64 s[2:3], 0x1d4000
	v_lshl_add_u64 v[120:121], v[20:21], 0, s[2:3]
	global_load_dword v74, v[120:121], off
	s_mov_b64 s[2:3], 0x1da000
	v_lshl_add_u64 v[122:123], v[20:21], 0, s[2:3]
	global_load_dword v75, v[122:123], off
	ds_read_b128 v[32:35], v30 offset:192
	ds_read_b128 v[36:39], v30 offset:4288
	ds_read_b128 v[40:43], v30 offset:8384
	ds_read_b128 v[44:47], v30 offset:12480
	ds_read_b128 v[48:51], v30 offset:16576
	s_waitcnt lgkmcnt(0)
	s_waitcnt vmcnt(31)
	v_fmac_f32_e32 v24, v76, v32
	v_fmac_f32_e32 v29, v76, v36
	v_fmac_f32_e32 v27, v76, v40
	v_fmac_f32_e32 v26, v76, v44
	v_fmac_f32_e32 v25, v76, v48
	s_waitcnt vmcnt(30)
	v_fmac_f32_e32 v24, v77, v33
	v_fmac_f32_e32 v29, v77, v37
	v_fmac_f32_e32 v27, v77, v41
	v_fmac_f32_e32 v26, v77, v45
	v_fmac_f32_e32 v25, v77, v49
	s_waitcnt vmcnt(29)
	v_fmac_f32_e32 v24, v78, v34
	v_fmac_f32_e32 v29, v78, v38
	v_fmac_f32_e32 v27, v78, v42
	v_fmac_f32_e32 v26, v78, v46
	v_fmac_f32_e32 v25, v78, v50
	s_waitcnt vmcnt(28)
	v_fmac_f32_e32 v24, v79, v35
	v_fmac_f32_e32 v29, v79, v39
	v_fmac_f32_e32 v27, v79, v43
	v_fmac_f32_e32 v26, v79, v47
	v_fmac_f32_e32 v25, v79, v51
	ds_read_b128 v[32:35], v30 offset:208
	ds_read_b128 v[36:39], v30 offset:4304
	ds_read_b128 v[40:43], v30 offset:8400
	ds_read_b128 v[44:47], v30 offset:12496
	ds_read_b128 v[48:51], v30 offset:16592
	s_waitcnt lgkmcnt(0)
	s_waitcnt vmcnt(27)
	v_fmac_f32_e32 v24, v80, v32
	v_fmac_f32_e32 v29, v80, v36
	v_fmac_f32_e32 v27, v80, v40
	v_fmac_f32_e32 v26, v80, v44
	v_fmac_f32_e32 v25, v80, v48
	s_waitcnt vmcnt(26)
	v_fmac_f32_e32 v24, v81, v33
	v_fmac_f32_e32 v29, v81, v37
	v_fmac_f32_e32 v27, v81, v41
	v_fmac_f32_e32 v26, v81, v45
	v_fmac_f32_e32 v25, v81, v49
	s_waitcnt vmcnt(25)
	v_fmac_f32_e32 v24, v82, v34
	v_fmac_f32_e32 v29, v82, v38
	v_fmac_f32_e32 v27, v82, v42
	v_fmac_f32_e32 v26, v82, v46
	v_fmac_f32_e32 v25, v82, v50
	s_waitcnt vmcnt(24)
	v_fmac_f32_e32 v24, v83, v35
	v_fmac_f32_e32 v29, v83, v39
	v_fmac_f32_e32 v27, v83, v43
	v_fmac_f32_e32 v26, v83, v47
	v_fmac_f32_e32 v25, v83, v51
	ds_read_b128 v[32:35], v30 offset:224
	ds_read_b128 v[36:39], v30 offset:4320
	ds_read_b128 v[40:43], v30 offset:8416
	ds_read_b128 v[44:47], v30 offset:12512
	ds_read_b128 v[48:51], v30 offset:16608
	s_waitcnt lgkmcnt(0)
	s_waitcnt vmcnt(23)
	v_fmac_f32_e32 v24, v84, v32
	v_fmac_f32_e32 v29, v84, v36
	v_fmac_f32_e32 v27, v84, v40
	v_fmac_f32_e32 v26, v84, v44
	v_fmac_f32_e32 v25, v84, v48
	s_waitcnt vmcnt(22)
	v_fmac_f32_e32 v24, v85, v33
	v_fmac_f32_e32 v29, v85, v37
	v_fmac_f32_e32 v27, v85, v41
	v_fmac_f32_e32 v26, v85, v45
	v_fmac_f32_e32 v25, v85, v49
	s_waitcnt vmcnt(21)
	v_fmac_f32_e32 v24, v86, v34
	v_fmac_f32_e32 v29, v86, v38
	v_fmac_f32_e32 v27, v86, v42
	v_fmac_f32_e32 v26, v86, v46
	v_fmac_f32_e32 v25, v86, v50
	s_waitcnt vmcnt(20)
	v_fmac_f32_e32 v24, v87, v35
	v_fmac_f32_e32 v29, v87, v39
	v_fmac_f32_e32 v27, v87, v43
	v_fmac_f32_e32 v26, v87, v47
	v_fmac_f32_e32 v25, v87, v51
	ds_read_b128 v[32:35], v30 offset:240
	ds_read_b128 v[36:39], v30 offset:4336
	ds_read_b128 v[40:43], v30 offset:8432
	ds_read_b128 v[44:47], v30 offset:12528
	ds_read_b128 v[48:51], v30 offset:16624
	s_waitcnt lgkmcnt(0)
	s_waitcnt vmcnt(19)
	v_fmac_f32_e32 v24, v88, v32
	v_fmac_f32_e32 v29, v88, v36
	v_fmac_f32_e32 v27, v88, v40
	v_fmac_f32_e32 v26, v88, v44
	v_fmac_f32_e32 v25, v88, v48
	s_waitcnt vmcnt(18)
	v_fmac_f32_e32 v24, v89, v33
	v_fmac_f32_e32 v29, v89, v37
	v_fmac_f32_e32 v27, v89, v41
	v_fmac_f32_e32 v26, v89, v45
	v_fmac_f32_e32 v25, v89, v49
	s_waitcnt vmcnt(17)
	v_fmac_f32_e32 v24, v90, v34
	v_fmac_f32_e32 v29, v90, v38
	v_fmac_f32_e32 v27, v90, v42
	v_fmac_f32_e32 v26, v90, v46
	v_fmac_f32_e32 v25, v90, v50
	s_waitcnt vmcnt(16)
	v_fmac_f32_e32 v24, v91, v35
	v_fmac_f32_e32 v29, v91, v39
	v_fmac_f32_e32 v27, v91, v43
	v_fmac_f32_e32 v26, v91, v47
	v_fmac_f32_e32 v25, v91, v51
	s_mov_b64 s[2:3], 0x1e0000
	v_lshl_add_u64 v[92:93], v[20:21], 0, s[2:3]
	global_load_dword v76, v[92:93], off
	s_mov_b64 s[2:3], 0x1e6000
	v_lshl_add_u64 v[94:95], v[20:21], 0, s[2:3]
	global_load_dword v77, v[94:95], off
	s_mov_b64 s[2:3], 0x1ec000
	v_lshl_add_u64 v[96:97], v[20:21], 0, s[2:3]
	global_load_dword v78, v[96:97], off
	s_mov_b64 s[2:3], 0x1f2000
	v_lshl_add_u64 v[98:99], v[20:21], 0, s[2:3]
	global_load_dword v79, v[98:99], off
	s_mov_b64 s[2:3], 0x1f8000
	v_lshl_add_u64 v[100:101], v[20:21], 0, s[2:3]
	global_load_dword v80, v[100:101], off
	s_mov_b64 s[2:3], 0x1fe000
	v_lshl_add_u64 v[102:103], v[20:21], 0, s[2:3]
	global_load_dword v81, v[102:103], off
	s_mov_b64 s[2:3], 0x204000
	v_lshl_add_u64 v[104:105], v[20:21], 0, s[2:3]
	global_load_dword v82, v[104:105], off
	s_mov_b64 s[2:3], 0x20a000
	v_lshl_add_u64 v[106:107], v[20:21], 0, s[2:3]
	global_load_dword v83, v[106:107], off
	s_mov_b64 s[2:3], 0x210000
	v_lshl_add_u64 v[108:109], v[20:21], 0, s[2:3]
	global_load_dword v84, v[108:109], off
	s_mov_b64 s[2:3], 0x216000
	v_lshl_add_u64 v[110:111], v[20:21], 0, s[2:3]
	global_load_dword v85, v[110:111], off
	s_mov_b64 s[2:3], 0x21c000
	v_lshl_add_u64 v[112:113], v[20:21], 0, s[2:3]
	global_load_dword v86, v[112:113], off
	s_mov_b64 s[2:3], 0x222000
	v_lshl_add_u64 v[114:115], v[20:21], 0, s[2:3]
	global_load_dword v87, v[114:115], off
	s_mov_b64 s[2:3], 0x228000
	v_lshl_add_u64 v[116:117], v[20:21], 0, s[2:3]
	global_load_dword v88, v[116:117], off
	s_mov_b64 s[2:3], 0x22e000
	v_lshl_add_u64 v[118:119], v[20:21], 0, s[2:3]
	global_load_dword v89, v[118:119], off
	s_mov_b64 s[2:3], 0x234000
	v_lshl_add_u64 v[120:121], v[20:21], 0, s[2:3]
	global_load_dword v90, v[120:121], off
	s_mov_b64 s[2:3], 0x23a000
	v_lshl_add_u64 v[122:123], v[20:21], 0, s[2:3]
	global_load_dword v91, v[122:123], off
	ds_read_b128 v[32:35], v30 offset:256
	ds_read_b128 v[36:39], v30 offset:4352
	ds_read_b128 v[40:43], v30 offset:8448
	ds_read_b128 v[44:47], v30 offset:12544
	ds_read_b128 v[48:51], v30 offset:16640
	s_waitcnt lgkmcnt(0)
	s_waitcnt vmcnt(31)
	v_fmac_f32_e32 v24, v60, v32
	v_fmac_f32_e32 v29, v60, v36
	v_fmac_f32_e32 v27, v60, v40
	v_fmac_f32_e32 v26, v60, v44
	v_fmac_f32_e32 v25, v60, v48
	s_waitcnt vmcnt(30)
	v_fmac_f32_e32 v24, v61, v33
	v_fmac_f32_e32 v29, v61, v37
	v_fmac_f32_e32 v27, v61, v41
	v_fmac_f32_e32 v26, v61, v45
	v_fmac_f32_e32 v25, v61, v49
	s_waitcnt vmcnt(29)
	v_fmac_f32_e32 v24, v62, v34
	v_fmac_f32_e32 v29, v62, v38
	v_fmac_f32_e32 v27, v62, v42
	v_fmac_f32_e32 v26, v62, v46
	v_fmac_f32_e32 v25, v62, v50
	s_waitcnt vmcnt(28)
	v_fmac_f32_e32 v24, v63, v35
	v_fmac_f32_e32 v29, v63, v39
	v_fmac_f32_e32 v27, v63, v43
	v_fmac_f32_e32 v26, v63, v47
	v_fmac_f32_e32 v25, v63, v51
	ds_read_b128 v[32:35], v30 offset:272
	ds_read_b128 v[36:39], v30 offset:4368
	ds_read_b128 v[40:43], v30 offset:8464
	ds_read_b128 v[44:47], v30 offset:12560
	ds_read_b128 v[48:51], v30 offset:16656
	s_waitcnt lgkmcnt(0)
	s_waitcnt vmcnt(27)
	v_fmac_f32_e32 v24, v64, v32
	v_fmac_f32_e32 v29, v64, v36
	v_fmac_f32_e32 v27, v64, v40
	v_fmac_f32_e32 v26, v64, v44
	v_fmac_f32_e32 v25, v64, v48
	s_waitcnt vmcnt(26)
	v_fmac_f32_e32 v24, v65, v33
	v_fmac_f32_e32 v29, v65, v37
	v_fmac_f32_e32 v27, v65, v41
	v_fmac_f32_e32 v26, v65, v45
	v_fmac_f32_e32 v25, v65, v49
	s_waitcnt vmcnt(25)
	v_fmac_f32_e32 v24, v66, v34
	v_fmac_f32_e32 v29, v66, v38
	v_fmac_f32_e32 v27, v66, v42
	v_fmac_f32_e32 v26, v66, v46
	v_fmac_f32_e32 v25, v66, v50
	s_waitcnt vmcnt(24)
	v_fmac_f32_e32 v24, v67, v35
	v_fmac_f32_e32 v29, v67, v39
	v_fmac_f32_e32 v27, v67, v43
	v_fmac_f32_e32 v26, v67, v47
	v_fmac_f32_e32 v25, v67, v51
	ds_read_b128 v[32:35], v30 offset:288
	ds_read_b128 v[36:39], v30 offset:4384
	ds_read_b128 v[40:43], v30 offset:8480
	ds_read_b128 v[44:47], v30 offset:12576
	ds_read_b128 v[48:51], v30 offset:16672
	s_waitcnt lgkmcnt(0)
	s_waitcnt vmcnt(23)
	v_fmac_f32_e32 v24, v68, v32
	v_fmac_f32_e32 v29, v68, v36
	v_fmac_f32_e32 v27, v68, v40
	v_fmac_f32_e32 v26, v68, v44
	v_fmac_f32_e32 v25, v68, v48
	s_waitcnt vmcnt(22)
	v_fmac_f32_e32 v24, v69, v33
	v_fmac_f32_e32 v29, v69, v37
	v_fmac_f32_e32 v27, v69, v41
	v_fmac_f32_e32 v26, v69, v45
	v_fmac_f32_e32 v25, v69, v49
	s_waitcnt vmcnt(21)
	v_fmac_f32_e32 v24, v70, v34
	v_fmac_f32_e32 v29, v70, v38
	v_fmac_f32_e32 v27, v70, v42
	v_fmac_f32_e32 v26, v70, v46
	v_fmac_f32_e32 v25, v70, v50
	s_waitcnt vmcnt(20)
	v_fmac_f32_e32 v24, v71, v35
	v_fmac_f32_e32 v29, v71, v39
	v_fmac_f32_e32 v27, v71, v43
	v_fmac_f32_e32 v26, v71, v47
	v_fmac_f32_e32 v25, v71, v51
	ds_read_b128 v[32:35], v30 offset:304
	ds_read_b128 v[36:39], v30 offset:4400
	ds_read_b128 v[40:43], v30 offset:8496
	ds_read_b128 v[44:47], v30 offset:12592
	ds_read_b128 v[48:51], v30 offset:16688
	s_waitcnt lgkmcnt(0)
	s_waitcnt vmcnt(19)
	v_fmac_f32_e32 v24, v72, v32
	v_fmac_f32_e32 v29, v72, v36
	v_fmac_f32_e32 v27, v72, v40
	v_fmac_f32_e32 v26, v72, v44
	v_fmac_f32_e32 v25, v72, v48
	s_waitcnt vmcnt(18)
	v_fmac_f32_e32 v24, v73, v33
	v_fmac_f32_e32 v29, v73, v37
	v_fmac_f32_e32 v27, v73, v41
	v_fmac_f32_e32 v26, v73, v45
	v_fmac_f32_e32 v25, v73, v49
	s_waitcnt vmcnt(17)
	v_fmac_f32_e32 v24, v74, v34
	v_fmac_f32_e32 v29, v74, v38
	v_fmac_f32_e32 v27, v74, v42
	v_fmac_f32_e32 v26, v74, v46
	v_fmac_f32_e32 v25, v74, v50
	s_waitcnt vmcnt(16)
	v_fmac_f32_e32 v24, v75, v35
	v_fmac_f32_e32 v29, v75, v39
	v_fmac_f32_e32 v27, v75, v43
	v_fmac_f32_e32 v26, v75, v47
	v_fmac_f32_e32 v25, v75, v51
	s_mov_b64 s[2:3], 0x240000
	v_lshl_add_u64 v[92:93], v[20:21], 0, s[2:3]
	global_load_dword v60, v[92:93], off
	s_mov_b64 s[2:3], 0x246000
	v_lshl_add_u64 v[94:95], v[20:21], 0, s[2:3]
	global_load_dword v61, v[94:95], off
	s_mov_b64 s[2:3], 0x24c000
	v_lshl_add_u64 v[96:97], v[20:21], 0, s[2:3]
	global_load_dword v62, v[96:97], off
	s_mov_b64 s[2:3], 0x252000
	v_lshl_add_u64 v[98:99], v[20:21], 0, s[2:3]
	global_load_dword v63, v[98:99], off
	s_mov_b64 s[2:3], 0x258000
	v_lshl_add_u64 v[100:101], v[20:21], 0, s[2:3]
	global_load_dword v64, v[100:101], off
	s_mov_b64 s[2:3], 0x25e000
	v_lshl_add_u64 v[102:103], v[20:21], 0, s[2:3]
	global_load_dword v65, v[102:103], off
	s_mov_b64 s[2:3], 0x264000
	v_lshl_add_u64 v[104:105], v[20:21], 0, s[2:3]
	global_load_dword v66, v[104:105], off
	s_mov_b64 s[2:3], 0x26a000
	v_lshl_add_u64 v[106:107], v[20:21], 0, s[2:3]
	global_load_dword v67, v[106:107], off
	s_mov_b64 s[2:3], 0x270000
	v_lshl_add_u64 v[108:109], v[20:21], 0, s[2:3]
	global_load_dword v68, v[108:109], off
	s_mov_b64 s[2:3], 0x276000
	v_lshl_add_u64 v[110:111], v[20:21], 0, s[2:3]
	global_load_dword v69, v[110:111], off
	s_mov_b64 s[2:3], 0x27c000
	v_lshl_add_u64 v[112:113], v[20:21], 0, s[2:3]
	global_load_dword v70, v[112:113], off
	s_mov_b64 s[2:3], 0x282000
	v_lshl_add_u64 v[114:115], v[20:21], 0, s[2:3]
	global_load_dword v71, v[114:115], off
	s_mov_b64 s[2:3], 0x288000
	v_lshl_add_u64 v[116:117], v[20:21], 0, s[2:3]
	global_load_dword v72, v[116:117], off
	s_mov_b64 s[2:3], 0x28e000
	v_lshl_add_u64 v[118:119], v[20:21], 0, s[2:3]
	global_load_dword v73, v[118:119], off
	s_mov_b64 s[2:3], 0x294000
	v_lshl_add_u64 v[120:121], v[20:21], 0, s[2:3]
	global_load_dword v74, v[120:121], off
	s_mov_b64 s[2:3], 0x29a000
	v_lshl_add_u64 v[122:123], v[20:21], 0, s[2:3]
	global_load_dword v75, v[122:123], off
	ds_read_b128 v[32:35], v30 offset:320
	ds_read_b128 v[36:39], v30 offset:4416
	ds_read_b128 v[40:43], v30 offset:8512
	ds_read_b128 v[44:47], v30 offset:12608
	ds_read_b128 v[48:51], v30 offset:16704
	s_waitcnt lgkmcnt(0)
	s_waitcnt vmcnt(31)
	v_fmac_f32_e32 v24, v76, v32
	v_fmac_f32_e32 v29, v76, v36
	v_fmac_f32_e32 v27, v76, v40
	v_fmac_f32_e32 v26, v76, v44
	v_fmac_f32_e32 v25, v76, v48
	s_waitcnt vmcnt(30)
	v_fmac_f32_e32 v24, v77, v33
	v_fmac_f32_e32 v29, v77, v37
	v_fmac_f32_e32 v27, v77, v41
	v_fmac_f32_e32 v26, v77, v45
	v_fmac_f32_e32 v25, v77, v49
	s_waitcnt vmcnt(29)
	v_fmac_f32_e32 v24, v78, v34
	v_fmac_f32_e32 v29, v78, v38
	v_fmac_f32_e32 v27, v78, v42
	v_fmac_f32_e32 v26, v78, v46
	v_fmac_f32_e32 v25, v78, v50
	s_waitcnt vmcnt(28)
	v_fmac_f32_e32 v24, v79, v35
	v_fmac_f32_e32 v29, v79, v39
	v_fmac_f32_e32 v27, v79, v43
	v_fmac_f32_e32 v26, v79, v47
	v_fmac_f32_e32 v25, v79, v51
	ds_read_b128 v[32:35], v30 offset:336
	ds_read_b128 v[36:39], v30 offset:4432
	ds_read_b128 v[40:43], v30 offset:8528
	ds_read_b128 v[44:47], v30 offset:12624
	ds_read_b128 v[48:51], v30 offset:16720
	s_waitcnt lgkmcnt(0)
	s_waitcnt vmcnt(27)
	v_fmac_f32_e32 v24, v80, v32
	v_fmac_f32_e32 v29, v80, v36
	v_fmac_f32_e32 v27, v80, v40
	v_fmac_f32_e32 v26, v80, v44
	v_fmac_f32_e32 v25, v80, v48
	s_waitcnt vmcnt(26)
	v_fmac_f32_e32 v24, v81, v33
	v_fmac_f32_e32 v29, v81, v37
	v_fmac_f32_e32 v27, v81, v41
	v_fmac_f32_e32 v26, v81, v45
	v_fmac_f32_e32 v25, v81, v49
	s_waitcnt vmcnt(25)
	v_fmac_f32_e32 v24, v82, v34
	v_fmac_f32_e32 v29, v82, v38
	v_fmac_f32_e32 v27, v82, v42
	v_fmac_f32_e32 v26, v82, v46
	v_fmac_f32_e32 v25, v82, v50
	s_waitcnt vmcnt(24)
	v_fmac_f32_e32 v24, v83, v35
	v_fmac_f32_e32 v29, v83, v39
	v_fmac_f32_e32 v27, v83, v43
	v_fmac_f32_e32 v26, v83, v47
	v_fmac_f32_e32 v25, v83, v51
	ds_read_b128 v[32:35], v30 offset:352
	ds_read_b128 v[36:39], v30 offset:4448
	ds_read_b128 v[40:43], v30 offset:8544
	ds_read_b128 v[44:47], v30 offset:12640
	ds_read_b128 v[48:51], v30 offset:16736
	s_waitcnt lgkmcnt(0)
	s_waitcnt vmcnt(23)
	v_fmac_f32_e32 v24, v84, v32
	v_fmac_f32_e32 v29, v84, v36
	v_fmac_f32_e32 v27, v84, v40
	v_fmac_f32_e32 v26, v84, v44
	v_fmac_f32_e32 v25, v84, v48
	s_waitcnt vmcnt(22)
	v_fmac_f32_e32 v24, v85, v33
	v_fmac_f32_e32 v29, v85, v37
	v_fmac_f32_e32 v27, v85, v41
	v_fmac_f32_e32 v26, v85, v45
	v_fmac_f32_e32 v25, v85, v49
	s_waitcnt vmcnt(21)
	v_fmac_f32_e32 v24, v86, v34
	v_fmac_f32_e32 v29, v86, v38
	v_fmac_f32_e32 v27, v86, v42
	v_fmac_f32_e32 v26, v86, v46
	v_fmac_f32_e32 v25, v86, v50
	s_waitcnt vmcnt(20)
	v_fmac_f32_e32 v24, v87, v35
	v_fmac_f32_e32 v29, v87, v39
	v_fmac_f32_e32 v27, v87, v43
	v_fmac_f32_e32 v26, v87, v47
	v_fmac_f32_e32 v25, v87, v51
	ds_read_b128 v[32:35], v30 offset:368
	ds_read_b128 v[36:39], v30 offset:4464
	ds_read_b128 v[40:43], v30 offset:8560
	ds_read_b128 v[44:47], v30 offset:12656
	ds_read_b128 v[48:51], v30 offset:16752
	s_waitcnt lgkmcnt(0)
	s_waitcnt vmcnt(19)
	v_fmac_f32_e32 v24, v88, v32
	v_fmac_f32_e32 v29, v88, v36
	v_fmac_f32_e32 v27, v88, v40
	v_fmac_f32_e32 v26, v88, v44
	v_fmac_f32_e32 v25, v88, v48
	s_waitcnt vmcnt(18)
	v_fmac_f32_e32 v24, v89, v33
	v_fmac_f32_e32 v29, v89, v37
	v_fmac_f32_e32 v27, v89, v41
	v_fmac_f32_e32 v26, v89, v45
	v_fmac_f32_e32 v25, v89, v49
	s_waitcnt vmcnt(17)
	v_fmac_f32_e32 v24, v90, v34
	v_fmac_f32_e32 v29, v90, v38
	v_fmac_f32_e32 v27, v90, v42
	v_fmac_f32_e32 v26, v90, v46
	v_fmac_f32_e32 v25, v90, v50
	s_waitcnt vmcnt(16)
	v_fmac_f32_e32 v24, v91, v35
	v_fmac_f32_e32 v29, v91, v39
	v_fmac_f32_e32 v27, v91, v43
	v_fmac_f32_e32 v26, v91, v47
	v_fmac_f32_e32 v25, v91, v51
	s_mov_b64 s[2:3], 0x2a0000
	v_lshl_add_u64 v[92:93], v[20:21], 0, s[2:3]
	global_load_dword v76, v[92:93], off
	s_mov_b64 s[2:3], 0x2a6000
	v_lshl_add_u64 v[94:95], v[20:21], 0, s[2:3]
	global_load_dword v77, v[94:95], off
	s_mov_b64 s[2:3], 0x2ac000
	v_lshl_add_u64 v[96:97], v[20:21], 0, s[2:3]
	global_load_dword v78, v[96:97], off
	s_mov_b64 s[2:3], 0x2b2000
	v_lshl_add_u64 v[98:99], v[20:21], 0, s[2:3]
	global_load_dword v79, v[98:99], off
	s_mov_b64 s[2:3], 0x2b8000
	v_lshl_add_u64 v[100:101], v[20:21], 0, s[2:3]
	global_load_dword v80, v[100:101], off
	s_mov_b64 s[2:3], 0x2be000
	v_lshl_add_u64 v[102:103], v[20:21], 0, s[2:3]
	global_load_dword v81, v[102:103], off
	s_mov_b64 s[2:3], 0x2c4000
	v_lshl_add_u64 v[104:105], v[20:21], 0, s[2:3]
	global_load_dword v82, v[104:105], off
	s_mov_b64 s[2:3], 0x2ca000
	v_lshl_add_u64 v[106:107], v[20:21], 0, s[2:3]
	global_load_dword v83, v[106:107], off
	s_mov_b64 s[2:3], 0x2d0000
	v_lshl_add_u64 v[108:109], v[20:21], 0, s[2:3]
	global_load_dword v84, v[108:109], off
	s_mov_b64 s[2:3], 0x2d6000
	v_lshl_add_u64 v[110:111], v[20:21], 0, s[2:3]
	global_load_dword v85, v[110:111], off
	s_mov_b64 s[2:3], 0x2dc000
	v_lshl_add_u64 v[112:113], v[20:21], 0, s[2:3]
	global_load_dword v86, v[112:113], off
	s_mov_b64 s[2:3], 0x2e2000
	v_lshl_add_u64 v[114:115], v[20:21], 0, s[2:3]
	global_load_dword v87, v[114:115], off
	s_mov_b64 s[2:3], 0x2e8000
	v_lshl_add_u64 v[116:117], v[20:21], 0, s[2:3]
	global_load_dword v88, v[116:117], off
	s_mov_b64 s[2:3], 0x2ee000
	v_lshl_add_u64 v[118:119], v[20:21], 0, s[2:3]
	global_load_dword v89, v[118:119], off
	s_mov_b64 s[2:3], 0x2f4000
	v_lshl_add_u64 v[120:121], v[20:21], 0, s[2:3]
	global_load_dword v90, v[120:121], off
	s_mov_b64 s[2:3], 0x2fa000
	v_lshl_add_u64 v[122:123], v[20:21], 0, s[2:3]
	global_load_dword v91, v[122:123], off
	ds_read_b128 v[32:35], v30 offset:384
	ds_read_b128 v[36:39], v30 offset:4480
	ds_read_b128 v[40:43], v30 offset:8576
	ds_read_b128 v[44:47], v30 offset:12672
	ds_read_b128 v[48:51], v30 offset:16768
	s_waitcnt lgkmcnt(0)
	s_waitcnt vmcnt(31)
	v_fmac_f32_e32 v24, v60, v32
	v_fmac_f32_e32 v29, v60, v36
	v_fmac_f32_e32 v27, v60, v40
	v_fmac_f32_e32 v26, v60, v44
	v_fmac_f32_e32 v25, v60, v48
	s_waitcnt vmcnt(30)
	v_fmac_f32_e32 v24, v61, v33
	v_fmac_f32_e32 v29, v61, v37
	v_fmac_f32_e32 v27, v61, v41
	v_fmac_f32_e32 v26, v61, v45
	v_fmac_f32_e32 v25, v61, v49
	s_waitcnt vmcnt(29)
	v_fmac_f32_e32 v24, v62, v34
	v_fmac_f32_e32 v29, v62, v38
	v_fmac_f32_e32 v27, v62, v42
	v_fmac_f32_e32 v26, v62, v46
	v_fmac_f32_e32 v25, v62, v50
	s_waitcnt vmcnt(28)
	v_fmac_f32_e32 v24, v63, v35
	v_fmac_f32_e32 v29, v63, v39
	v_fmac_f32_e32 v27, v63, v43
	v_fmac_f32_e32 v26, v63, v47
	v_fmac_f32_e32 v25, v63, v51
	ds_read_b128 v[32:35], v30 offset:400
	ds_read_b128 v[36:39], v30 offset:4496
	ds_read_b128 v[40:43], v30 offset:8592
	ds_read_b128 v[44:47], v30 offset:12688
	ds_read_b128 v[48:51], v30 offset:16784
	s_waitcnt lgkmcnt(0)
	s_waitcnt vmcnt(27)
	v_fmac_f32_e32 v24, v64, v32
	v_fmac_f32_e32 v29, v64, v36
	v_fmac_f32_e32 v27, v64, v40
	v_fmac_f32_e32 v26, v64, v44
	v_fmac_f32_e32 v25, v64, v48
	s_waitcnt vmcnt(26)
	v_fmac_f32_e32 v24, v65, v33
	v_fmac_f32_e32 v29, v65, v37
	v_fmac_f32_e32 v27, v65, v41
	v_fmac_f32_e32 v26, v65, v45
	v_fmac_f32_e32 v25, v65, v49
	s_waitcnt vmcnt(25)
	v_fmac_f32_e32 v24, v66, v34
	v_fmac_f32_e32 v29, v66, v38
	v_fmac_f32_e32 v27, v66, v42
	v_fmac_f32_e32 v26, v66, v46
	v_fmac_f32_e32 v25, v66, v50
	s_waitcnt vmcnt(24)
	v_fmac_f32_e32 v24, v67, v35
	v_fmac_f32_e32 v29, v67, v39
	v_fmac_f32_e32 v27, v67, v43
	v_fmac_f32_e32 v26, v67, v47
	v_fmac_f32_e32 v25, v67, v51
	ds_read_b128 v[32:35], v30 offset:416
	ds_read_b128 v[36:39], v30 offset:4512
	ds_read_b128 v[40:43], v30 offset:8608
	ds_read_b128 v[44:47], v30 offset:12704
	ds_read_b128 v[48:51], v30 offset:16800
	s_waitcnt lgkmcnt(0)
	s_waitcnt vmcnt(23)
	v_fmac_f32_e32 v24, v68, v32
	v_fmac_f32_e32 v29, v68, v36
	v_fmac_f32_e32 v27, v68, v40
	v_fmac_f32_e32 v26, v68, v44
	v_fmac_f32_e32 v25, v68, v48
	s_waitcnt vmcnt(22)
	v_fmac_f32_e32 v24, v69, v33
	v_fmac_f32_e32 v29, v69, v37
	v_fmac_f32_e32 v27, v69, v41
	v_fmac_f32_e32 v26, v69, v45
	v_fmac_f32_e32 v25, v69, v49
	s_waitcnt vmcnt(21)
	v_fmac_f32_e32 v24, v70, v34
	v_fmac_f32_e32 v29, v70, v38
	v_fmac_f32_e32 v27, v70, v42
	v_fmac_f32_e32 v26, v70, v46
	v_fmac_f32_e32 v25, v70, v50
	s_waitcnt vmcnt(20)
	v_fmac_f32_e32 v24, v71, v35
	v_fmac_f32_e32 v29, v71, v39
	v_fmac_f32_e32 v27, v71, v43
	v_fmac_f32_e32 v26, v71, v47
	v_fmac_f32_e32 v25, v71, v51
	ds_read_b128 v[32:35], v30 offset:432
	ds_read_b128 v[36:39], v30 offset:4528
	ds_read_b128 v[40:43], v30 offset:8624
	ds_read_b128 v[44:47], v30 offset:12720
	ds_read_b128 v[48:51], v30 offset:16816
	s_waitcnt lgkmcnt(0)
	s_waitcnt vmcnt(19)
	v_fmac_f32_e32 v24, v72, v32
	v_fmac_f32_e32 v29, v72, v36
	v_fmac_f32_e32 v27, v72, v40
	v_fmac_f32_e32 v26, v72, v44
	v_fmac_f32_e32 v25, v72, v48
	s_waitcnt vmcnt(18)
	v_fmac_f32_e32 v24, v73, v33
	v_fmac_f32_e32 v29, v73, v37
	v_fmac_f32_e32 v27, v73, v41
	v_fmac_f32_e32 v26, v73, v45
	v_fmac_f32_e32 v25, v73, v49
	s_waitcnt vmcnt(17)
	v_fmac_f32_e32 v24, v74, v34
	v_fmac_f32_e32 v29, v74, v38
	v_fmac_f32_e32 v27, v74, v42
	v_fmac_f32_e32 v26, v74, v46
	v_fmac_f32_e32 v25, v74, v50
	s_waitcnt vmcnt(16)
	v_fmac_f32_e32 v24, v75, v35
	v_fmac_f32_e32 v29, v75, v39
	v_fmac_f32_e32 v27, v75, v43
	v_fmac_f32_e32 v26, v75, v47
	v_fmac_f32_e32 v25, v75, v51
	ds_read_b128 v[32:35], v30 offset:448
	ds_read_b128 v[36:39], v30 offset:4544
	ds_read_b128 v[40:43], v30 offset:8640
	ds_read_b128 v[44:47], v30 offset:12736
	ds_read_b128 v[48:51], v30 offset:16832
	s_waitcnt lgkmcnt(0)
	s_waitcnt vmcnt(15)
	v_fmac_f32_e32 v24, v76, v32
	v_fmac_f32_e32 v29, v76, v36
	v_fmac_f32_e32 v27, v76, v40
	v_fmac_f32_e32 v26, v76, v44
	v_fmac_f32_e32 v25, v76, v48
	s_waitcnt vmcnt(14)
	v_fmac_f32_e32 v24, v77, v33
	v_fmac_f32_e32 v29, v77, v37
	v_fmac_f32_e32 v27, v77, v41
	v_fmac_f32_e32 v26, v77, v45
	v_fmac_f32_e32 v25, v77, v49
	s_waitcnt vmcnt(13)
	v_fmac_f32_e32 v24, v78, v34
	v_fmac_f32_e32 v29, v78, v38
	v_fmac_f32_e32 v27, v78, v42
	v_fmac_f32_e32 v26, v78, v46
	v_fmac_f32_e32 v25, v78, v50
	s_waitcnt vmcnt(12)
	v_fmac_f32_e32 v24, v79, v35
	v_fmac_f32_e32 v29, v79, v39
	v_fmac_f32_e32 v27, v79, v43
	v_fmac_f32_e32 v26, v79, v47
	v_fmac_f32_e32 v25, v79, v51
	ds_read_b128 v[32:35], v30 offset:464
	ds_read_b128 v[36:39], v30 offset:4560
	ds_read_b128 v[40:43], v30 offset:8656
	ds_read_b128 v[44:47], v30 offset:12752
	ds_read_b128 v[48:51], v30 offset:16848
	s_waitcnt lgkmcnt(0)
	s_waitcnt vmcnt(11)
	v_fmac_f32_e32 v24, v80, v32
	v_fmac_f32_e32 v29, v80, v36
	v_fmac_f32_e32 v27, v80, v40
	v_fmac_f32_e32 v26, v80, v44
	v_fmac_f32_e32 v25, v80, v48
	s_waitcnt vmcnt(10)
	v_fmac_f32_e32 v24, v81, v33
	v_fmac_f32_e32 v29, v81, v37
	v_fmac_f32_e32 v27, v81, v41
	v_fmac_f32_e32 v26, v81, v45
	v_fmac_f32_e32 v25, v81, v49
	s_waitcnt vmcnt(9)
	v_fmac_f32_e32 v24, v82, v34
	v_fmac_f32_e32 v29, v82, v38
	v_fmac_f32_e32 v27, v82, v42
	v_fmac_f32_e32 v26, v82, v46
	v_fmac_f32_e32 v25, v82, v50
	s_waitcnt vmcnt(8)
	v_fmac_f32_e32 v24, v83, v35
	v_fmac_f32_e32 v29, v83, v39
	v_fmac_f32_e32 v27, v83, v43
	v_fmac_f32_e32 v26, v83, v47
	v_fmac_f32_e32 v25, v83, v51
	ds_read_b128 v[32:35], v30 offset:480
	ds_read_b128 v[36:39], v30 offset:4576
	ds_read_b128 v[40:43], v30 offset:8672
	ds_read_b128 v[44:47], v30 offset:12768
	ds_read_b128 v[48:51], v30 offset:16864
	s_waitcnt lgkmcnt(0)
	s_waitcnt vmcnt(7)
	v_fmac_f32_e32 v24, v84, v32
	v_fmac_f32_e32 v29, v84, v36
	v_fmac_f32_e32 v27, v84, v40
	v_fmac_f32_e32 v26, v84, v44
	v_fmac_f32_e32 v25, v84, v48
	s_waitcnt vmcnt(6)
	v_fmac_f32_e32 v24, v85, v33
	v_fmac_f32_e32 v29, v85, v37
	v_fmac_f32_e32 v27, v85, v41
	v_fmac_f32_e32 v26, v85, v45
	v_fmac_f32_e32 v25, v85, v49
	s_waitcnt vmcnt(5)
	v_fmac_f32_e32 v24, v86, v34
	v_fmac_f32_e32 v29, v86, v38
	v_fmac_f32_e32 v27, v86, v42
	v_fmac_f32_e32 v26, v86, v46
	v_fmac_f32_e32 v25, v86, v50
	s_waitcnt vmcnt(4)
	v_fmac_f32_e32 v24, v87, v35
	v_fmac_f32_e32 v29, v87, v39
	v_fmac_f32_e32 v27, v87, v43
	v_fmac_f32_e32 v26, v87, v47
	v_fmac_f32_e32 v25, v87, v51
	ds_read_b128 v[32:35], v30 offset:496
	ds_read_b128 v[36:39], v30 offset:4592
	ds_read_b128 v[40:43], v30 offset:8688
	ds_read_b128 v[44:47], v30 offset:12784
	ds_read_b128 v[48:51], v30 offset:16880
	s_waitcnt lgkmcnt(0)
	s_waitcnt vmcnt(3)
	v_fmac_f32_e32 v24, v88, v32
	v_fmac_f32_e32 v29, v88, v36
	v_fmac_f32_e32 v27, v88, v40
	v_fmac_f32_e32 v26, v88, v44
	v_fmac_f32_e32 v25, v88, v48
	s_waitcnt vmcnt(2)
	v_fmac_f32_e32 v24, v89, v33
	v_fmac_f32_e32 v29, v89, v37
	v_fmac_f32_e32 v27, v89, v41
	v_fmac_f32_e32 v26, v89, v45
	v_fmac_f32_e32 v25, v89, v49
	s_waitcnt vmcnt(1)
	v_fmac_f32_e32 v24, v90, v34
	v_fmac_f32_e32 v29, v90, v38
	v_fmac_f32_e32 v27, v90, v42
	v_fmac_f32_e32 v26, v90, v46
	v_fmac_f32_e32 v25, v90, v50
	s_waitcnt vmcnt(0)
	v_fmac_f32_e32 v24, v91, v35
	v_fmac_f32_e32 v29, v91, v39
	v_fmac_f32_e32 v27, v91, v43
	v_fmac_f32_e32 v26, v91, v47
	v_fmac_f32_e32 v25, v91, v51
	v_add_u32_e32 v4, 0x5000, v17
	s_barrier
	ds_write2_b32 v4, v24, v29 offset1:32
	ds_write2_b32 v4, v27, v26 offset0:64 offset1:96
	ds_write_b32 v17, v25 offset:20992
	s_waitcnt lgkmcnt(0)
	s_barrier
	s_and_saveexec_b64 s[36:37], vcc
	s_cbranch_execz .LBB0_867
	s_mul_i32 s2, s39, 0x1800
	s_add_i32 s2, s2, s38
	v_or_b32_e32 v4, s2, v0
	v_ashrrev_i32_e32 v5, 31, v4
	v_lshl_add_u64 v[4:5], v[4:5], 2, s[10:11]
	global_load_dword v6, v[4:5], off
	v_add_u32_e32 v7, v3, v1
	v_add_u32_e32 v4, 0x5000, v7
	ds_read2_b32 v[4:5], v4 offset1:160
	v_readlane_b32 s2, v251, 63
	v_readlane_b32 s3, v252, 0
	s_waitcnt vmcnt(0) lgkmcnt(0)
	v_add_f32_e32 v4, v6, v4
	v_add_f32_e32 v6, v4, v5
	v_add_u32_e32 v4, 0x5400, v7
	ds_read2_b32 v[4:5], v4 offset0:64 offset1:224
	s_waitcnt lgkmcnt(0)
	v_add_f32_e32 v4, v6, v4
	v_add_f32_e32 v6, v4, v5
	v_add_u32_e32 v4, 0x5a00, v7
	ds_read2_b32 v[4:5], v4 offset1:160
	s_waitcnt lgkmcnt(0)
	v_add_f32_e32 v4, v6, v4
	v_add_f32_e32 v6, v4, v5
	v_add_u32_e32 v4, 0x5e00, v7
	ds_read2_b32 v[4:5], v4 offset0:64 offset1:224
	s_waitcnt lgkmcnt(0)
	v_add_f32_e32 v4, v6, v4
	v_add_f32_e32 v8, v4, v5
	v_mad_u64_u32 v[4:5], s[20:21], s39, 5, v[16:17]
	v_mov_b64_e32 v[6:7], s[2:3]
	s_ashr_i32 s39, s38, 31
	v_mad_i64_i32 v[4:5], s[20:21], v4, s97, v[6:7]
	v_lshl_add_u64 v[4:5], s[38:39], 2, v[4:5]
	v_lshlrev_b32_e32 v6, 2, v0
	v_mov_b32_e32 v7, v2
	v_lshl_add_u64 v[4:5], v[4:5], 0, v[6:7]
	global_store_dword v[4:5], v8, off
	s_branch .LBB0_867
